# FB2: same as FB with the hand-written barrier spin bounds raised to 1M polls (robustness only)
# speedup vs baseline: 1.0037x; 1.0037x over previous
.Lfbp_mspin:
	s_sleep 1
	global_load_dword v4, v[122:123], off sc1
	s_waitcnt vmcnt(0)
	v_readfirstlane_b32 s6, v4
	s_nop 3
	s_cmp_lg_u32 s6, s9
	s_cbranch_scc1 .Lfbp_acq
	s_add_u32 s4, s4, 1
	s_cmp_lt_u32 s4, 0x100000
	s_cbranch_scc1 .Lfbp_mspin
	s_branch .Lfbp_acq

.Lfbp_lspin:
	global_load_dword v4, v1, s[4:5] sc1
	s_waitcnt vmcnt(0)
	v_readfirstlane_b32 s6, v4
	s_nop 3
	s_cmp_ge_u32 s6, s10
	s_cbranch_scc1 .Lfbp_rel
	s_sleep 1
	s_add_u32 s11, s11, 1
	s_cmp_lt_u32 s11, 0x100000
	s_cbranch_scc1 .Lfbp_lspin

.Lgba_spin:
	s_sleep 1
	global_load_dword v3, v1, s[4:5] offset:128 sc1
	s_waitcnt vmcnt(0)
	v_readfirstlane_b32 s6, v3
	s_nop 3
	s_cmp_lg_u32 s6, s7
	s_cbranch_scc1 .Lgba_done
	s_add_u32 s8, s8, 1
	s_cmp_lt_u32 s8, 0x100000
	s_cbranch_scc1 .Lgba_spin
